# diff-attn v128 max-free loop: LDS-DMA block issued at different points by wave halves (waves 0-3 between QK and PV, waves 4-7 after PV MFMA 6); on top of v1
# speedup vs baseline: 1.0087x; 1.0087x over previous
.LBB0_798:
	v_readlane_b32 s101, v253, 6
	s_mov_b32 s8, s36
	s_mov_b32 s6, s10
	s_mov_b32 s7, s35
	v_add_f32_e32 v98, v82, v83
	v_add_f32_e32 v98, v84, v98
	v_add_f32_e32 v98, v85, v98
	v_add_f32_e32 v98, v86, v98
	v_add_f32_e32 v98, v87, v98
	v_cvt_pk_bf16_f32 v158, v82, v83
	v_cvt_pk_bf16_f32 v159, v84, v85
	v_lshl_add_u32 v201, s9, 1, v214
	s_waitcnt lgkmcnt(7)
	v_mfma_f32_32x32x16_bf16 v[114:129], v[186:189], v[154:157], 0
	s_nop 0
	v_add_f32_e32 v82, v88, v98
	v_add_f32_e32 v82, v89, v82
	v_add_f32_e32 v82, v90, v82
	v_add_f32_e32 v82, v91, v82
	v_cvt_pk_bf16_f32 v160, v86, v87
	v_cvt_pk_bf16_f32 v161, v88, v89
	s_waitcnt lgkmcnt(6)
	v_mfma_f32_32x32x16_bf16 v[98:113], v[174:177], v[154:157], 0
	v_add_f32_e32 v82, v92, v82
	v_add_f32_e32 v82, v93, v82
	v_add_f32_e32 v82, v94, v82
	v_add_f32_e32 v86, v95, v82
	v_cvt_pk_bf16_f32 v146, v90, v91
	v_cvt_pk_bf16_f32 v147, v92, v93
	s_waitcnt lgkmcnt(5)
	v_mfma_f32_32x32x16_bf16 v[114:129], v[190:193], v[150:153], v[114:129]
	ds_read_b64_tr_b16 v[82:83], v201 offset:24576
	ds_read_b64_tr_b16 v[84:85], v201 offset:25088
	v_add_f32_e32 v86, v96, v86
	v_add_f32_e32 v86, v97, v86
	v_add_f32_e32 v86, v66, v86
	v_add_f32_e32 v90, v67, v86
	v_cvt_pk_bf16_f32 v148, v94, v95
	v_cvt_pk_bf16_f32 v149, v96, v97
	s_waitcnt lgkmcnt(6)
	v_mfma_f32_32x32x16_bf16 v[98:113], v[178:181], v[150:153], v[98:113]
	ds_read_b64_tr_b16 v[86:87], v201 offset:28672
	ds_read_b64_tr_b16 v[88:89], v201 offset:29184
	v_add_f32_e32 v90, v68, v90
	v_add_f32_e32 v90, v69, v90
	v_add_f32_e32 v90, v70, v90
	v_add_f32_e32 v90, v71, v90
	v_cvt_pk_bf16_f32 v138, v66, v67
	v_cvt_pk_bf16_f32 v139, v68, v69
	s_waitcnt lgkmcnt(7)
	v_mfma_f32_32x32x16_bf16 v[114:129], v[182:185], v[142:145], v[114:129]
	ds_read_b64_tr_b16 v[66:67], v201 offset:32768
	ds_read_b64_tr_b16 v[68:69], v201 offset:33280
	v_add_f32_e32 v90, v72, v90
	v_add_f32_e32 v90, v73, v90
	v_add_f32_e32 v90, v74, v90
	v_add_f32_e32 v90, v75, v90
	v_cvt_pk_bf16_f32 v140, v70, v71
	v_cvt_pk_bf16_f32 v141, v72, v73
	s_waitcnt lgkmcnt(8)
	v_mfma_f32_32x32x16_bf16 v[98:113], v[166:169], v[142:145], v[98:113]
	ds_read_b64_tr_b16 v[70:71], v201 offset:36864
	ds_read_b64_tr_b16 v[72:73], v201 offset:37376
	v_add_f32_e32 v90, v76, v90
	v_add_f32_e32 v90, v77, v90
	v_add_f32_e32 v90, v78, v90
	v_add_f32_e32 v90, v79, v90
	v_cvt_pk_bf16_f32 v130, v74, v75
	v_cvt_pk_bf16_f32 v131, v76, v77
	s_waitcnt lgkmcnt(9)
	v_mfma_f32_32x32x16_bf16 v[114:129], v[170:173], v[134:137], v[114:129]
	ds_read_b64_tr_b16 v[74:75], v201 offset:25600
	ds_read_b64_tr_b16 v[76:77], v201 offset:26112
	v_add_f32_e32 v90, v80, v90
	v_add_f32_e32 v90, v81, v90
	v_add_f32_e32 v200, 0, v90
	v_cvt_pk_bf16_f32 v132, v78, v79
	v_cvt_pk_bf16_f32 v133, v80, v81
	s_waitcnt lgkmcnt(10)
	v_mfma_f32_32x32x16_bf16 v[98:113], v[162:165], v[134:137], v[98:113]
	s_cmpk_lt_u32 s101, 0x100
	s_cbranch_scc0 .Lmy_skipA0
	v_lshl_add_u64 v[202:203], v[194:195], 0, s[4:5]
	s_add_i32 s100, s35, s33
	v_lshl_add_u64 v[204:205], v[202:203], 0, s[12:13]
	s_mov_b32 m0, s100
	s_nop 0
	global_load_lds_dwordx4 v[204:205], off
	v_lshl_add_u64 v[218:219], v[196:197], 0, s[4:5]
	s_lshl_b32 s100, s36, 1
	v_lshl_add_u64 v[222:223], v[218:219], 0, s[14:15]
	s_add_i32 s100, s100, s34
	s_mov_b32 m0, s100
	s_nop 0
	global_load_lds_dwordx4 v[222:223], off
	v_lshl_add_u64 v[220:221], v[198:199], 0, s[4:5]
	v_lshl_add_u64 v[224:225], v[220:221], 0, s[14:15]
	s_addk_i32 s100, 0x2000
	s_mov_b32 m0, s100
	s_nop 0
	global_load_lds_dwordx4 v[224:225], off
.Lmy_skipA0:
	s_waitcnt lgkmcnt(8)
	v_mfma_f32_32x32x16_bf16 v[34:49], v[158:161], v[82:85], v[34:49]
	v_exp_f32_e32 v114, v114
	v_exp_f32_e32 v115, v115
	ds_read_b64_tr_b16 v[78:79], v201 offset:29696
	ds_read_b64_tr_b16 v[80:81], v201 offset:30208
	s_waitcnt lgkmcnt(8)
	v_mfma_f32_32x32x16_bf16 v[50:65], v[158:161], v[86:89], v[50:65]
	v_exp_f32_e32 v116, v116
	v_exp_f32_e32 v117, v117
	ds_read_b64_tr_b16 v[82:83], v201 offset:33792
	ds_read_b64_tr_b16 v[84:85], v201 offset:34304
	s_waitcnt lgkmcnt(8)
	v_mfma_f32_32x32x16_bf16 v[2:17], v[158:161], v[66:69], v[2:17]
	v_exp_f32_e32 v118, v118
	v_exp_f32_e32 v119, v119
	ds_read_b64_tr_b16 v[86:87], v201 offset:37888
	ds_read_b64_tr_b16 v[88:89], v201 offset:38400
	s_waitcnt lgkmcnt(8)
	v_mfma_f32_32x32x16_bf16 v[18:33], v[158:161], v[70:73], v[18:33]
	v_exp_f32_e32 v120, v120
	v_exp_f32_e32 v121, v121
	ds_read_b64_tr_b16 v[70:71], v201 offset:26624
	ds_read_b64_tr_b16 v[72:73], v201 offset:27136
	v_add_u32_e32 v94, s8, v212
	ds_read_b128 v[90:93], v94
	ds_read_b128 v[66:69], v94 offset:512
	s_waitcnt lgkmcnt(10)
	v_mfma_f32_32x32x16_bf16 v[34:49], v[146:149], v[74:77], v[34:49]
	v_exp_f32_e32 v122, v122
	v_exp_f32_e32 v123, v123
	ds_read_b64_tr_b16 v[74:75], v201 offset:30720
	ds_read_b64_tr_b16 v[76:77], v201 offset:31232
	s_waitcnt lgkmcnt(10)
	v_mfma_f32_32x32x16_bf16 v[50:65], v[146:149], v[78:81], v[50:65]
	v_exp_f32_e32 v124, v124
	v_exp_f32_e32 v125, v125
	s_cmpk_lt_u32 s101, 0x100
	s_cbranch_scc1 .Lmy_skipB0
	v_lshl_add_u64 v[202:203], v[194:195], 0, s[4:5]
	s_add_i32 s100, s35, s33
	v_lshl_add_u64 v[204:205], v[202:203], 0, s[12:13]
	s_mov_b32 m0, s100
	s_nop 0
	global_load_lds_dwordx4 v[204:205], off
	v_lshl_add_u64 v[218:219], v[196:197], 0, s[4:5]
	s_lshl_b32 s100, s36, 1
	v_lshl_add_u64 v[222:223], v[218:219], 0, s[14:15]
	s_add_i32 s100, s100, s34
	s_mov_b32 m0, s100
	s_nop 0
	global_load_lds_dwordx4 v[222:223], off
	v_lshl_add_u64 v[220:221], v[198:199], 0, s[4:5]
	v_lshl_add_u64 v[224:225], v[220:221], 0, s[14:15]
	s_addk_i32 s100, 0x2000
	s_mov_b32 m0, s100
	s_nop 0
	global_load_lds_dwordx4 v[224:225], off
; #define WAIT_BAR(N) asm volatile("s_waitcnt vmcnt(" #N ") lgkmcnt(0)\n\ts_barrier":::"memory")
;   #define RESC() do{ if(resc){ asm volatile("s_waitcnt lgkmcnt(0)":::"memory"); \
;       _Pragma("unroll") for(int d_=0;d_<2;++d_) _Pragma("unroll") for(int r=0;r<16;++r)o[d_][r]*=wsf[crow(r,hi)]; } }while(0)
;   #define ROT() do{sl_prev=sl_cur;sl_cur=sl_next;sl_next=(sl_next==(NSLOT-1)*SLOTB)?0:sl_next+SLOTB;}while(0)
;   #define RESC() do{ if(resc){ asm volatile("s_waitcnt lgkmcnt(0)":::"memory"); \
;       _Pragma("unroll") for(int d_=0;d_<4;++d_) _Pragma("unroll") for(int r=0;r<16;++r)o[d_][r]*=wsf[crow(r,hi)]; } }while(0)
;   #define ROT() do{sl_prev=sl_cur;sl_cur=sl_next;sl_next=(sl_next==(NSLOT-1)*SLOTB)?0:sl_next+SLOTB;}while(0)
; template<int THRL,bool NOMAX=false> __device__ __forceinline__ void attn_unit_v128(const bf16*Qu,int qp,const bf16*__restrict__ Kh,int kp,const bf16*__restrict__ Vh,int vp,bf16*Ou,int op,int NT,char*shm,int tid_in){
;     ...
;   int t=1;
;   for(;t+5<NT;t+=2){
;     STEP(pB0,pB1,pA0,pA1,t,true,true,true);     WAIT_BAR(3); RESC(); ROT();
;     STEP(pA0,pA1,pB0,pB1,t+1,true,true,true);   WAIT_BAR(3); RESC(); ROT();
.Lmy_skipB0:
	ds_read_b64_tr_b16 v[78:79], v201 offset:34816
	ds_read_b64_tr_b16 v[80:81], v201 offset:35328
	s_waitcnt lgkmcnt(10)
	v_mfma_f32_32x32x16_bf16 v[2:17], v[146:149], v[82:85], v[2:17]
	v_exp_f32_e32 v126, v126
	v_exp_f32_e32 v127, v127
	ds_read_b64_tr_b16 v[82:83], v201 offset:38912
	ds_read_b64_tr_b16 v[84:85], v201 offset:39424
	ds_read_b128 v[168:171], v94 offset:2048
	ds_read_b128 v[172:175], v94 offset:2560
	s_waitcnt lgkmcnt(12)
	v_mfma_f32_32x32x16_bf16 v[18:33], v[146:149], v[86:89], v[18:33]
	v_exp_f32_e32 v128, v128
	v_exp_f32_e32 v129, v129
	ds_read_b64_tr_b16 v[86:87], v201 offset:27648
	ds_read_b64_tr_b16 v[88:89], v201 offset:28160
	s_waitcnt lgkmcnt(12)
	v_mfma_f32_32x32x16_bf16 v[34:49], v[138:141], v[70:73], v[34:49]
	v_exp_f32_e32 v98, v98
	v_exp_f32_e32 v99, v99
	ds_read_b64_tr_b16 v[70:71], v201 offset:31744
	ds_read_b64_tr_b16 v[72:73], v201 offset:32256
	s_waitcnt lgkmcnt(10)
	v_mfma_f32_32x32x16_bf16 v[50:65], v[138:141], v[74:77], v[50:65]
	v_exp_f32_e32 v100, v100
	v_exp_f32_e32 v101, v101
	ds_read_b64_tr_b16 v[74:75], v201 offset:35840
	ds_read_b64_tr_b16 v[76:77], v201 offset:36352
	ds_read_b128 v[176:179], v94 offset:4096
	ds_read_b128 v[180:183], v94 offset:4608
	s_waitcnt lgkmcnt(12)
	v_mfma_f32_32x32x16_bf16 v[2:17], v[138:141], v[78:81], v[2:17]
	v_exp_f32_e32 v102, v102
	v_exp_f32_e32 v103, v103
	ds_read_b64_tr_b16 v[78:79], v201 offset:39936
	ds_read_b64_tr_b16 v[80:81], v201 offset:40448
	s_waitcnt lgkmcnt(12)
	v_mfma_f32_32x32x16_bf16 v[18:33], v[138:141], v[82:85], v[18:33]
	v_exp_f32_e32 v104, v104
	v_exp_f32_e32 v105, v105
	s_waitcnt lgkmcnt(8)
	v_mfma_f32_32x32x16_bf16 v[34:49], v[130:133], v[86:89], v[34:49]
	v_exp_f32_e32 v106, v106
	v_exp_f32_e32 v107, v107
	ds_read_b128 v[184:187], v94 offset:6144
	ds_read_b128 v[188:191], v94 offset:6656
	s_waitcnt lgkmcnt(8)
	v_mfma_f32_32x32x16_bf16 v[50:65], v[130:133], v[70:73], v[50:65]
	v_exp_f32_e32 v108, v108
	v_exp_f32_e32 v109, v109
	s_waitcnt lgkmcnt(6)
	v_mfma_f32_32x32x16_bf16 v[2:17], v[130:133], v[74:77], v[2:17]
	v_exp_f32_e32 v110, v110
	v_exp_f32_e32 v111, v111
	s_waitcnt lgkmcnt(2)
	v_mfma_f32_32x32x16_bf16 v[18:33], v[130:133], v[78:81], v[18:33]
	v_exp_f32_e32 v112, v112
	v_exp_f32_e32 v113, v113
	s_waitcnt vmcnt(3) lgkmcnt(0)
	s_barrier
	s_add_i32 s9, s36, 0x2000
	s_cmpk_lg_i32 s36, 0x4000
	s_cselect_b32 s35, s9, 0
	v_mfma_f32_32x32x16_bf16 v[82:97], v[90:93], v[154:157], 0
	v_add_f32_e32 v70, v114, v115
	v_add_f32_e32 v70, v116, v70
	v_add_f32_e32 v70, v117, v70
	v_add_f32_e32 v70, v118, v70
	v_add_f32_e32 v70, v119, v70
	v_cvt_pk_bf16_f32 v158, v114, v115
	v_cvt_pk_bf16_f32 v159, v116, v117
	v_lshl_add_u32 v201, s7, 1, v214
	s_nop 0
	v_add_f32_e32 v70, v120, v70
	v_add_f32_e32 v70, v121, v70
	v_add_f32_e32 v70, v122, v70
	v_add_f32_e32 v114, v123, v70
	v_mfma_f32_32x32x16_bf16 v[66:81], v[66:69], v[154:157], 0
	v_cvt_pk_bf16_f32 v160, v118, v119
	v_cvt_pk_bf16_f32 v161, v120, v121
	v_mfma_f32_32x32x16_bf16 v[82:97], v[168:171], v[150:153], v[82:97]
	v_add_f32_e32 v114, v124, v114
	v_add_f32_e32 v114, v125, v114
	v_add_f32_e32 v114, v126, v114
	v_add_f32_e32 v118, v127, v114
	v_cvt_pk_bf16_f32 v146, v122, v123
	v_cvt_pk_bf16_f32 v147, v124, v125
	ds_read_b64_tr_b16 v[114:115], v201 offset:24576
	ds_read_b64_tr_b16 v[116:117], v201 offset:25088
	v_mfma_f32_32x32x16_bf16 v[66:81], v[172:175], v[150:153], v[66:81]
	v_add_f32_e32 v118, v128, v118
	v_add_f32_e32 v118, v129, v118
	v_add_f32_e32 v118, v98, v118
	v_add_f32_e32 v122, v99, v118
	v_cvt_pk_bf16_f32 v148, v126, v127
	v_cvt_pk_bf16_f32 v149, v128, v129
	ds_read_b64_tr_b16 v[118:119], v201 offset:28672
	ds_read_b64_tr_b16 v[120:121], v201 offset:29184
	v_mfma_f32_32x32x16_bf16 v[82:97], v[176:179], v[142:145], v[82:97]
	v_add_f32_e32 v122, v100, v122
	v_add_f32_e32 v122, v101, v122
	v_add_f32_e32 v122, v102, v122
	v_add_f32_e32 v122, v103, v122
	v_cvt_pk_bf16_f32 v138, v98, v99
	v_cvt_pk_bf16_f32 v139, v100, v101
	ds_read_b64_tr_b16 v[98:99], v201 offset:32768
	ds_read_b64_tr_b16 v[100:101], v201 offset:33280
	v_mfma_f32_32x32x16_bf16 v[66:81], v[180:183], v[142:145], v[66:81]
	v_add_f32_e32 v122, v104, v122
	v_add_f32_e32 v122, v105, v122
	v_add_f32_e32 v122, v106, v122
	v_add_f32_e32 v122, v107, v122
	v_cvt_pk_bf16_f32 v140, v102, v103
	v_cvt_pk_bf16_f32 v141, v104, v105
	ds_read_b64_tr_b16 v[102:103], v201 offset:36864
	ds_read_b64_tr_b16 v[104:105], v201 offset:37376
	s_waitcnt lgkmcnt(9)
	v_mfma_f32_32x32x16_bf16 v[82:97], v[184:187], v[134:137], v[82:97]
	v_add_f32_e32 v122, v108, v122
	v_add_f32_e32 v122, v109, v122
	v_add_f32_e32 v122, v110, v122
	v_add_f32_e32 v122, v111, v122
	v_cvt_pk_bf16_f32 v130, v106, v107
	v_cvt_pk_bf16_f32 v131, v108, v109
	ds_read_b64_tr_b16 v[106:107], v201 offset:25600
	ds_read_b64_tr_b16 v[108:109], v201 offset:26112
	s_waitcnt lgkmcnt(10)
	v_mfma_f32_32x32x16_bf16 v[66:81], v[188:191], v[134:137], v[66:81]
	v_add_f32_e32 v122, v112, v122
	v_add_f32_e32 v122, v113, v122
	v_add_f32_e32 v122, 0, v122
	v_cvt_pk_bf16_f32 v132, v110, v111
	v_cvt_pk_bf16_f32 v133, v112, v113
	s_cmpk_lt_u32 s101, 0x100
	s_cbranch_scc0 .Lmy_skipA1
	s_add_i32 s100, s36, s33
	v_lshl_add_u64 v[228:229], v[202:203], 0, s[18:19]
	s_mov_b32 m0, s100
	s_nop 0
	global_load_lds_dwordx4 v[228:229], off
	s_lshl_b32 s100, s35, 1
	v_lshl_add_u64 v[230:231], v[218:219], 0, s[16:17]
	s_add_i32 s100, s100, s34
	s_mov_b32 m0, s100
	s_nop 0
	global_load_lds_dwordx4 v[230:231], off
	v_lshl_add_u64 v[232:233], v[220:221], 0, s[16:17]
	s_addk_i32 s100, 0x2000
	s_mov_b32 m0, s100
	s_nop 0
	global_load_lds_dwordx4 v[232:233], off
; #define WAIT_BAR(N) asm volatile("s_waitcnt vmcnt(" #N ") lgkmcnt(0)\n\ts_barrier":::"memory")
;   #define RESC() do{ if(resc){ asm volatile("s_waitcnt lgkmcnt(0)":::"memory"); \
;       _Pragma("unroll") for(int d_=0;d_<2;++d_) _Pragma("unroll") for(int r=0;r<16;++r)o[d_][r]*=wsf[crow(r,hi)]; } }while(0)
;   #define ROT() do{sl_prev=sl_cur;sl_cur=sl_next;sl_next=(sl_next==(NSLOT-1)*SLOTB)?0:sl_next+SLOTB;}while(0)
;   #define RESC() do{ if(resc){ asm volatile("s_waitcnt lgkmcnt(0)":::"memory"); \
;       _Pragma("unroll") for(int d_=0;d_<4;++d_) _Pragma("unroll") for(int r=0;r<16;++r)o[d_][r]*=wsf[crow(r,hi)]; } }while(0)
;   #define ROT() do{sl_prev=sl_cur;sl_cur=sl_next;sl_next=(sl_next==(NSLOT-1)*SLOTB)?0:sl_next+SLOTB;}while(0)
; template<int THRL,bool NOMAX=false> __device__ __forceinline__ void attn_unit_v128(const bf16*Qu,int qp,const bf16*__restrict__ Kh,int kp,const bf16*__restrict__ Vh,int vp,bf16*Ou,int op,int NT,char*shm,int tid_in){
;     ...
;   int t=1;
;   for(;t+5<NT;t+=2){
;     STEP(pB0,pB1,pA0,pA1,t,true,true,true);     WAIT_BAR(3); RESC(); ROT();
;     STEP(pA0,pA1,pB0,pB1,t+1,true,true,true);   WAIT_BAR(3); RESC(); ROT();
;   }
.Lmy_skipA1:
	s_waitcnt lgkmcnt(8)
	v_mfma_f32_32x32x16_bf16 v[34:49], v[158:161], v[114:117], v[34:49]
	v_exp_f32_e32 v82, v82
	v_exp_f32_e32 v83, v83
	ds_read_b64_tr_b16 v[110:111], v201 offset:29696
	ds_read_b64_tr_b16 v[112:113], v201 offset:30208
	s_waitcnt lgkmcnt(8)
	v_mfma_f32_32x32x16_bf16 v[50:65], v[158:161], v[118:121], v[50:65]
	v_exp_f32_e32 v84, v84
	v_exp_f32_e32 v85, v85
	ds_read_b64_tr_b16 v[114:115], v201 offset:33792
	ds_read_b64_tr_b16 v[116:117], v201 offset:34304
	s_waitcnt lgkmcnt(8)
	v_mfma_f32_32x32x16_bf16 v[2:17], v[158:161], v[98:101], v[2:17]
	v_exp_f32_e32 v86, v86
	v_exp_f32_e32 v87, v87
	ds_read_b64_tr_b16 v[98:99], v201 offset:37888
	ds_read_b64_tr_b16 v[100:101], v201 offset:38400
	s_waitcnt lgkmcnt(8)
	v_mfma_f32_32x32x16_bf16 v[18:33], v[158:161], v[102:105], v[18:33]
	v_exp_f32_e32 v88, v88
	v_exp_f32_e32 v89, v89
	ds_read_b64_tr_b16 v[102:103], v201 offset:26624
	ds_read_b64_tr_b16 v[104:105], v201 offset:27136
	v_add_u32_e32 v118, s35, v212
	ds_read_b128 v[186:189], v118
	ds_read_b128 v[174:177], v118 offset:512
	s_waitcnt lgkmcnt(10)
	v_mfma_f32_32x32x16_bf16 v[34:49], v[146:149], v[106:109], v[34:49]
	v_exp_f32_e32 v90, v90
	v_exp_f32_e32 v91, v91
	ds_read_b64_tr_b16 v[106:107], v201 offset:30720
	ds_read_b64_tr_b16 v[108:109], v201 offset:31232
	s_waitcnt lgkmcnt(10)
	v_mfma_f32_32x32x16_bf16 v[50:65], v[146:149], v[110:113], v[50:65]
	v_exp_f32_e32 v92, v92
	v_exp_f32_e32 v93, v93
	s_cmpk_lt_u32 s101, 0x100
	s_cbranch_scc1 .Lmy_skipB1
	s_add_i32 s100, s36, s33
	v_lshl_add_u64 v[228:229], v[202:203], 0, s[18:19]
	s_mov_b32 m0, s100
	s_nop 0
	global_load_lds_dwordx4 v[228:229], off
	s_lshl_b32 s100, s35, 1
	v_lshl_add_u64 v[230:231], v[218:219], 0, s[16:17]
	s_add_i32 s100, s100, s34
	s_mov_b32 m0, s100
	s_nop 0
	global_load_lds_dwordx4 v[230:231], off
	v_lshl_add_u64 v[232:233], v[220:221], 0, s[16:17]
	s_addk_i32 s100, 0x2000
	s_mov_b32 m0, s100
	s_nop 0
	global_load_lds_dwordx4 v[232:233], off
.Lmy_skipB1:
	ds_read_b64_tr_b16 v[110:111], v201 offset:34816
	ds_read_b64_tr_b16 v[112:113], v201 offset:35328
	s_waitcnt lgkmcnt(10)
	v_mfma_f32_32x32x16_bf16 v[2:17], v[146:149], v[114:117], v[2:17]
	v_exp_f32_e32 v94, v94
	v_exp_f32_e32 v95, v95
	ds_read_b64_tr_b16 v[114:115], v201 offset:38912
	ds_read_b64_tr_b16 v[116:117], v201 offset:39424
	ds_read_b128 v[190:193], v118 offset:2048
	ds_read_b128 v[178:181], v118 offset:2560
	s_waitcnt lgkmcnt(12)
	v_mfma_f32_32x32x16_bf16 v[18:33], v[146:149], v[98:101], v[18:33]
	v_exp_f32_e32 v96, v96
	v_exp_f32_e32 v97, v97
	ds_read_b64_tr_b16 v[98:99], v201 offset:27648
	ds_read_b64_tr_b16 v[100:101], v201 offset:28160
	s_waitcnt lgkmcnt(12)
	v_mfma_f32_32x32x16_bf16 v[34:49], v[138:141], v[102:105], v[34:49]
	v_exp_f32_e32 v66, v66
	v_exp_f32_e32 v67, v67
	ds_read_b64_tr_b16 v[102:103], v201 offset:31744
	ds_read_b64_tr_b16 v[104:105], v201 offset:32256
	s_waitcnt lgkmcnt(10)
	v_mfma_f32_32x32x16_bf16 v[50:65], v[138:141], v[106:109], v[50:65]
	v_exp_f32_e32 v68, v68
	v_exp_f32_e32 v69, v69
	ds_read_b64_tr_b16 v[106:107], v201 offset:35840
	ds_read_b64_tr_b16 v[108:109], v201 offset:36352
	ds_read_b128 v[182:185], v118 offset:4096
	ds_read_b128 v[166:169], v118 offset:4608
	s_waitcnt lgkmcnt(12)
	v_mfma_f32_32x32x16_bf16 v[2:17], v[138:141], v[110:113], v[2:17]
	v_exp_f32_e32 v70, v70
	v_exp_f32_e32 v71, v71
	ds_read_b64_tr_b16 v[110:111], v201 offset:39936
	ds_read_b64_tr_b16 v[112:113], v201 offset:40448
	s_waitcnt lgkmcnt(12)
	v_mfma_f32_32x32x16_bf16 v[18:33], v[138:141], v[114:117], v[18:33]
	v_exp_f32_e32 v72, v72
	v_exp_f32_e32 v73, v73
	s_waitcnt lgkmcnt(8)
	v_mfma_f32_32x32x16_bf16 v[34:49], v[130:133], v[98:101], v[34:49]
	v_exp_f32_e32 v74, v74
	v_exp_f32_e32 v75, v75
	ds_read_b128 v[170:173], v118 offset:6144
	ds_read_b128 v[162:165], v118 offset:6656
	s_waitcnt lgkmcnt(8)
	v_mfma_f32_32x32x16_bf16 v[50:65], v[130:133], v[102:105], v[50:65]
	v_exp_f32_e32 v76, v76
	v_exp_f32_e32 v77, v77
	s_waitcnt lgkmcnt(6)
	v_mfma_f32_32x32x16_bf16 v[2:17], v[130:133], v[106:109], v[2:17]
	v_exp_f32_e32 v78, v78
	v_exp_f32_e32 v79, v79
	s_waitcnt lgkmcnt(2)
	v_mfma_f32_32x32x16_bf16 v[18:33], v[130:133], v[110:113], v[18:33]
	v_exp_f32_e32 v80, v80
	v_exp_f32_e32 v81, v81
	s_add_i32 s7, s35, 0x2000
	s_cmpk_lg_i32 s35, 0x4000
	s_mov_b32 s9, s36
	s_cselect_b32 s36, s7, 0
	s_add_i32 s10, s6, 2
	s_waitcnt vmcnt(3) lgkmcnt(0)
	s_barrier
	s_add_u32 s4, s4, 0x20000
	v_add_f32_e32 v98, v210, v200
	s_addc_u32 s5, s5, 0
	s_cmp_ge_u32 s10, s75
	v_add_f32_e32 v210, v98, v122
	s_cbranch_scc0 .LBB0_798
	s_add_i32 s86, s6, -3
	s_add_i32 s4, s86, 1
	s_cmp_ge_u32 s4, s75
	s_mov_b64 s[4:5], -1
	s_cbranch_scc0 .LBB0_802
	s_branch .LBB0_801
